# v66 plus residual-stream bf16 conversion fused into the first norm phase (prologue X pass removed)
# speedup vs baseline: 1.0003x; 1.0003x over previous
.LBB0_121:
	s_lshl_b32 s4, s22, 9
	s_add_i32 s4, s4, s86
	v_add_u32_e32 v0, s4, v68
	s_mov_b32 s4, 0x300000
	v_cmp_gt_i32_e32 vcc, s4, v0
	s_and_saveexec_b64 s[8:9], vcc
	v_readlane_b32 s94, v255, 3
	v_readlane_b32 s95, v255, 4
	s_branch .LBB0_126
	s_load_dwordx4 s[4:7], s[28:29], 0x0
	s_add_u32 s10, s26, 0x400000
	s_addc_u32 s11, s27, 0
	s_lshl_b32 s12, s3, 9
	v_ashrrev_i32_e32 v1, 31, v0
	s_ashr_i32 s13, s12, 31
	v_lshlrev_b64 v[2:3], 5, v[0:1]
	s_waitcnt lgkmcnt(0)
	v_lshl_add_u64 v[2:3], s[4:5], 0, v[2:3]
	s_lshl_b64 s[4:5], s[12:13], 5
	s_mov_b64 s[14:15], 0
	s_mov_b32 s3, 0x1fffff
	v_mov_b32_e32 v5, 0
	s_mov_b32 s18, 0x2fffff
	s_branch .LBB0_124

.LBB0_194:
	v_lshl_add_u64 v[64:65], v[96:97], 2, s[38:39]
	s_mov_b64 s[20:21], 0x1000
	global_load_dwordx4 v[92:95], v[64:65], off
	global_load_dwordx4 v[88:91], v[64:65], off offset:16
	global_load_dwordx4 v[84:87], v[64:65], off offset:2048
	global_load_dwordx4 v[80:83], v[64:65], off offset:2064
	v_lshl_add_u64 v[66:67], v[64:65], 0, s[20:21]
	v_add_co_u32_e32 v68, vcc, s90, v64
	s_mov_b64 s[20:21], 0x1800
	s_nop 0
	v_addc_co_u32_e32 v69, vcc, 0, v65, vcc
	v_lshl_add_u64 v[64:65], v[64:65], 0, s[20:21]
	global_load_dwordx4 v[76:79], v[68:69], off
	global_load_dwordx4 v[72:75], v[66:67], off offset:16
	s_nop 0
	global_load_dwordx4 v[68:71], v[68:69], off offset:2048
	s_nop 0
	global_load_dwordx4 v[64:67], v[64:65], off offset:16
	s_lshl_b64 s[38:39], s[4:5], 12
	s_waitcnt vmcnt(0)
	v_lshl_add_u64 v[124:125], v[112:113], 0, s[38:39]
	v_cvt_pk_bf16_f32 v126, v92, v93
	v_cvt_pk_bf16_f32 v127, v94, v95
	v_cvt_pk_bf16_f32 v128, v88, v89
	v_cvt_pk_bf16_f32 v129, v90, v91
	v_cvt_pk_bf16_f32 v130, v84, v85
	v_cvt_pk_bf16_f32 v131, v86, v87
	v_cvt_pk_bf16_f32 v132, v80, v81
	v_cvt_pk_bf16_f32 v133, v82, v83
	v_cvt_pk_bf16_f32 v134, v76, v77
	v_cvt_pk_bf16_f32 v135, v78, v79
	v_cvt_pk_bf16_f32 v136, v72, v73
	v_cvt_pk_bf16_f32 v137, v74, v75
	v_cvt_pk_bf16_f32 v138, v68, v69
	v_cvt_pk_bf16_f32 v139, v70, v71
	v_cvt_pk_bf16_f32 v140, v64, v65
	v_cvt_pk_bf16_f32 v141, v66, v67
	global_store_dwordx4 v[124:125], v[126:129], off offset:-2048
	global_store_dwordx4 v[124:125], v[130:133], off offset:-1024
	global_store_dwordx4 v[124:125], v[134:137], off
	global_store_dwordx4 v[124:125], v[138:141], off offset:1024
